# phase 3 item start: first K/V tile + mask-word loads issued before the Q-row loads, band bias load kept in flight until the common wait
# baseline (speedup 1.0000x reference)
; __device__ __forceinline__ void attn_tile(const bool BAND, AttnSmem& sm, u16* Qg, int qtok0, int hd, int nw, const u16* __restrict__ Kg, ...
;     ...
;   const int kt_lo = BAND ? (c_first - 8 > 0 ? c_first - 8 : 0) : 0;
;   if (BAND) {
;     for (int e = tid; e < 257; e += 512) sm.bias[e] = bias_tab[e * 8 + hd] * LOG2E;
;   }
;   bf16x8 qf0, qf1, qf2, qf3;
;   u16* qrow = Qg + (size_t)(qtok0 + 32 * wave + r) * 512 + hd * 64;
;   const float csc = 0.125f * LOG2E;
;   if (wact) {
;     ...
;     LOADQ(qf0, 0) LOADQ(qf1, 1) LOADQ(qf2, 2) LOADQ(qf3, 3)
;     ...
;   }
;   const bool usemask = !BAND && wact;
;   const u64* mrow = usemask ? maskrow0 + (size_t)(32 * wave + r) * mld + 4 * h : nullptr;
;   u64 mw0 = 0, mw1 = 0, mw2 = 0, mw3 = 0, nx0 = 0, nx1 = 0, nx2 = 0, nx3 = 0;
;   if (usemask) { nx0 = mrow[0]; nx1 = mrow[1]; nx2 = mrow[2]; nx3 = mrow[3]; }
;   f32x16 o0, o1;
; #pragma unroll
;   for (int i = 0; i < 16; i++) { o0[i] = 0.f; o1[i] = 0.f; }
;   f32v2 ls2 = {0.f, 0.f};
;   const int lrow = tid >> 3, lcol = (tid & 7) * 8;
;   const u16* kptr = Kg + (size_t)(kt_lo * 64 + lrow) * 64 + lcol;
;   const u16* vptr = VTg + (size_t)kt_lo * 4096 + lrow * 64 + lcol;
;   uint4 kv = *(const uint4*)kptr;
;   uint4 vv = *(const uint4*)vptr;
;   *(uint4*)&sm.K[0][lrow][lcol] = kv;
;   *(uint4*)&sm.VT[0][lrow][lcol] = vv;
;   if (kt_lo < c_last) {
;     kptr += 64 * 64; vptr += 4096;
;     kv = *(const uint4*)kptr;
;     vv = *(const uint4*)vptr;
;   }
;   __syncthreads();
.LBB0_615:
	v_or_b32_e32 v2, s37, v145
	v_readlane_b32 s68, v239, 16
	v_lshlrev_b32_e32 v2, 2, v2
	v_readlane_b32 s80, v239, 28
	v_readlane_b32 s81, v239, 29
	v_readlane_b32 s69, v239, 17
	v_readlane_b32 s70, v239, 18
	v_readlane_b32 s71, v239, 19
	v_readlane_b32 s72, v239, 20
	v_readlane_b32 s73, v239, 21
	global_load_dword v35, v2, s[80:81]
	v_readlane_b32 s74, v239, 22
	v_readlane_b32 s75, v239, 23
	v_readlane_b32 s76, v239, 24
	v_readlane_b32 s77, v239, 25
	v_readlane_b32 s78, v239, 26
	v_readlane_b32 s79, v239, 27
	v_readlane_b32 s82, v239, 30
	v_readlane_b32 s83, v239, 31
.LBB0_616:
	s_or_b64 exec, exec, s[6:7]
	v_add_u32_e32 v114, s20, v146
	v_lshlrev_b64 v[2:3], 10, v[114:115]
	v_lshl_add_u64 v[2:3], s[28:29], 0, v[2:3]
	s_lshl_b32 s20, s37, 7
	v_cmp_le_u32_e64 s[8:9], s35, v1
	v_cmp_gt_u32_e64 s[6:7], s35, v1
	v_lshl_add_u64 v[126:127], v[2:3], 0, s[20:21]
	v_mul_u32_u24_e32 v114, s34, v146
	v_lshl_add_u64 v[2:3], v[114:115], 3, s[30:31]
	v_mov_b64_e32 v[100:101], 0
	s_nor_b64 s[28:29], s[26:27], s[8:9]
	v_lshl_add_u64 v[128:129], v[2:3], 0, v[120:121]
	v_mov_b64_e32 v[98:99], v[100:101]
	v_mov_b64_e32 v[104:105], v[100:101]
	v_mov_b64_e32 v[102:103], v[100:101]
	s_and_saveexec_b64 s[30:31], s[28:29]
	s_cbranch_execz .LBB0_620
	global_load_dwordx4 v[98:101], v[128:129], off offset:16
	global_load_dwordx4 v[102:105], v[128:129], off
.LBB0_620:
	s_or_b64 exec, exec, s[30:31]
	s_lshl_b32 s20, s35, 5
	s_add_i32 s20, s36, s20
	s_sub_i32 s20, s20, 32
	s_lshr_b32 s68, s20, 6
	s_lshr_b32 s20, s36, 6
	v_sub_u32_e64 v2, s20, 8 clamp
	s_and_b64 s[30:31], s[26:27], exec
	v_readfirstlane_b32 s20, v2
	s_cselect_b32 s30, s20, 0
	s_lshl_b32 s20, s30, 6
	v_add_u32_e32 v114, s20, v147
	v_lshlrev_b64 v[2:3], 7, v[114:115]
	s_mov_b32 s31, s21
	v_lshl_add_u64 v[2:3], s[10:11], 0, v[2:3]
	s_lshl_b64 s[10:11], s[30:31], 13
	s_add_u32 s10, s12, s10
	s_addc_u32 s11, s13, s11
	v_lshl_add_u64 v[130:131], v[2:3], 0, v[122:123]
	v_lshl_add_u64 v[2:3], s[10:11], 0, v[124:125]
	v_lshl_add_u64 v[132:133], v[2:3], 0, v[122:123]
	global_load_dwordx4 v[106:109], v[130:131], off
	global_load_dwordx4 v[110:113], v[132:133], off
	s_and_saveexec_b64 s[28:29], s[6:7]
	s_cbranch_execz .LBB0_618
	v_mov_b32_e32 v119, v115
	v_lshl_add_u64 v[14:15], v[126:127], 0, v[118:119]
	global_load_dwordx4 v[2:5], v[14:15], off
	global_load_dwordx4 v[6:9], v[14:15], off offset:32
	global_load_dwordx4 v[10:13], v[14:15], off offset:64
	s_nop 0
	global_load_dwordx4 v[14:17], v[14:15], off offset:96
	s_waitcnt vmcnt(0)
	v_lshlrev_b32_e32 v18, 16, v2
	v_and_b32_e32 v19, 0xffff0000, v2
	v_lshlrev_b32_e32 v2, 16, v3
	v_and_b32_e32 v3, 0xffff0000, v3
	v_lshlrev_b32_e32 v20, 16, v4
	v_and_b32_e32 v21, 0xffff0000, v4
	v_lshlrev_b32_e32 v4, 16, v5
	v_and_b32_e32 v5, 0xffff0000, v5
	v_lshlrev_b32_e32 v22, 16, v6
	v_and_b32_e32 v23, 0xffff0000, v6
	v_lshlrev_b32_e32 v6, 16, v7
	v_and_b32_e32 v7, 0xffff0000, v7
	v_lshlrev_b32_e32 v24, 16, v8
	v_and_b32_e32 v25, 0xffff0000, v8
	v_lshlrev_b32_e32 v8, 16, v9
	v_and_b32_e32 v9, 0xffff0000, v9
	v_lshlrev_b32_e32 v26, 16, v10
	v_and_b32_e32 v27, 0xffff0000, v10
	v_lshlrev_b32_e32 v10, 16, v11
	v_and_b32_e32 v11, 0xffff0000, v11
	v_lshlrev_b32_e32 v28, 16, v12
	v_and_b32_e32 v29, 0xffff0000, v12
	v_lshlrev_b32_e32 v12, 16, v13
	v_and_b32_e32 v13, 0xffff0000, v13
	v_lshlrev_b32_e32 v30, 16, v14
	v_and_b32_e32 v31, 0xffff0000, v14
	v_lshlrev_b32_e32 v14, 16, v15
	v_and_b32_e32 v15, 0xffff0000, v15
	v_lshlrev_b32_e32 v32, 16, v16
	v_and_b32_e32 v33, 0xffff0000, v16
	v_lshlrev_b32_e32 v16, 16, v17
	v_and_b32_e32 v17, 0xffff0000, v17
	v_pk_mul_f32 v[18:19], v[18:19], s[22:23] op_sel_hi:[1,0]
	v_pk_mul_f32 v[2:3], v[2:3], s[22:23] op_sel_hi:[1,0]
	v_pk_mul_f32 v[20:21], v[20:21], s[22:23] op_sel_hi:[1,0]
	v_pk_mul_f32 v[4:5], v[4:5], s[22:23] op_sel_hi:[1,0]
	v_pk_mul_f32 v[22:23], v[22:23], s[22:23] op_sel_hi:[1,0]
	v_pk_mul_f32 v[6:7], v[6:7], s[22:23] op_sel_hi:[1,0]
	v_pk_mul_f32 v[24:25], v[24:25], s[22:23] op_sel_hi:[1,0]
	v_pk_mul_f32 v[8:9], v[8:9], s[22:23] op_sel_hi:[1,0]
	v_pk_mul_f32 v[26:27], v[26:27], s[22:23] op_sel_hi:[1,0]
	v_pk_mul_f32 v[10:11], v[10:11], s[22:23] op_sel_hi:[1,0]
	v_pk_mul_f32 v[28:29], v[28:29], s[22:23] op_sel_hi:[1,0]
	v_pk_mul_f32 v[12:13], v[12:13], s[22:23] op_sel_hi:[1,0]
	v_pk_mul_f32 v[30:31], v[30:31], s[22:23] op_sel_hi:[1,0]
	v_pk_mul_f32 v[14:15], v[14:15], s[22:23] op_sel_hi:[1,0]
	v_pk_mul_f32 v[32:33], v[32:33], s[22:23] op_sel_hi:[1,0]
	v_pk_mul_f32 v[16:17], v[16:17], s[22:23] op_sel_hi:[1,0]
	v_cvt_pk_bf16_f32 v94, v18, v19
	v_cvt_pk_bf16_f32 v95, v2, v3
	v_cvt_pk_bf16_f32 v96, v20, v21
	v_cvt_pk_bf16_f32 v97, v4, v5
	v_cvt_pk_bf16_f32 v90, v22, v23
	v_cvt_pk_bf16_f32 v91, v6, v7
	v_cvt_pk_bf16_f32 v92, v24, v25
	v_cvt_pk_bf16_f32 v93, v8, v9
	v_cvt_pk_bf16_f32 v86, v26, v27
	v_cvt_pk_bf16_f32 v87, v10, v11
	v_cvt_pk_bf16_f32 v88, v28, v29
	v_cvt_pk_bf16_f32 v89, v12, v13
	v_cvt_pk_bf16_f32 v82, v30, v31
	v_cvt_pk_bf16_f32 v83, v14, v15
	v_cvt_pk_bf16_f32 v84, v32, v33
	v_cvt_pk_bf16_f32 v85, v16, v17
.LBB0_618:
	s_or_b64 exec, exec, s[28:29]
	s_nor_b64 s[28:29], s[26:27], s[8:9]
	s_and_b64 vcc, s[26:27], s[4:5]
	s_waitcnt vmcnt(0)
	s_and_saveexec_b64 vcc, vcc
	v_mul_f32_e32 v35, 0x3fb8aa3b, v35
	ds_write_b32 v144, v35 offset:36864
	s_or_b64 exec, exec, vcc
	s_cmp_ge_u32 s30, s68
	s_waitcnt vmcnt(0)
	ds_write_b128 v148, v[106:109]
	ds_write_b128 v148, v[110:113] offset:18432
	s_cbranch_scc1 .LBB0_622
	v_add_co_u32_e32 v2, vcc, 0x2000, v130
	s_nop 1
	v_addc_co_u32_e32 v3, vcc, 0, v131, vcc
	global_load_dwordx4 v[106:109], v[2:3], off
	v_add_co_u32_e32 v2, vcc, 0x2000, v132
	v_lshl_add_u64 v[130:131], v[130:131], 0, s[24:25]
	s_nop 0
	v_addc_co_u32_e32 v3, vcc, 0, v133, vcc
	global_load_dwordx4 v[110:113], v[2:3], off
	v_lshl_add_u64 v[132:133], v[132:133], 0, s[24:25]
